# scan: transposed LDS images read with ds_read_b64_tr_b16, row-major BB/KB, 6 producer waves
# speedup vs baseline: 1.0311x; 1.0124x over previous
; __device__ __forceinline__ int otid() { int t = threadIdx.x; asm volatile("" : "+v"(t)); return t; }
; __device__ __forceinline__ int obid() { int b = blockIdx.x; asm volatile("" : "+s"(b)); return b; }
; __device__ __forceinline__ void phase_scan2(const Params& p, int l, LAS unsigned char* lds) {
;     ...
;     const int tid = otid(), wid = tid >> 6, lane = tid & 63, fr = lane & 15, fq = lane >> 4;
;     constexpr int NCH = SEQ / 16, NRD = (NCH + SC_NP - 1) / SC_NP;
;     for (int job = obid(); job < 256; job += gridDim.x) {
;         const int bh = job >> 2, rg = job & 3, b = bh >> 3, h = bh & 7;
;         const size_t tok0 = (size_t)b * SEQ;
;         const int pw = wid - 3, j = lane;
.Lsc_entry:
	s_mov_b32 s13, s5
	v_and_b32_e32 v0, 63, v183
	v_and_b32_e32 v1, 15, v183
	v_bfe_u32 v2, v183, 4, 2
	v_lshrrev_b32_e32 v4, 6, v183
	s_nop 0
	v_readfirstlane_b32 s25, v4
	v_lshlrev_b32_e32 v6, 5, v1
	v_lshl_add_u32 v6, v2, 3, v6
	v_lshrrev_b32_e32 v4, 2, v1
	v_lshl_add_u32 v4, v2, 2, v4
	v_and_b32_e32 v7, 3, v1
	v_lshlrev_b32_e32 v7, 3, v7
	v_lshl_add_u32 v7, v4, 5, v7
	s_add_u32 s26, s74, 0xc000000
	s_addc_u32 s27, s75, 0
	s_add_u32 s36, s74, 0x13000000
	s_addc_u32 s37, s75, 0
	s_add_u32 s38, s74, 0xa000000
	s_addc_u32 s39, s75, 0
	s_add_u32 s46, s74, 0x11000000
	s_addc_u32 s47, s75, 0

; #define LAS __attribute__((address_space(3)))
; __device__ __forceinline__ float bf2f(bf16_t b) { return __uint_as_float(((unsigned)b) << 16); }
; __device__ __forceinline__ bf16_t bf1(float x) { return (bf16_t)(pk_bf16(x, 0.f) & 0xffffu); }
; __device__ __forceinline__ void phase_scan2(const Params& p, int l, LAS unsigned char* lds) {
;     ...
;         const float kkc = k_k[h * 64 + j], kac = k_a[h * 64 + j], rkc = r_k[h * 64 + j];
;         unsigned short kraw[16], araw[16], rraw[16]; _Float16 eraw[16]; unsigned short vraw[4];
; #pragma unroll
;         for (int t = 0; t < 16; ++t) { kraw[t] = 0; araw[t] = 0; rraw[t] = 0; eraw[t] = (_Float16)0; }
; #pragma unroll
;         for (int q = 0; q < 4; ++q) vraw[q] = 0;
;         auto pload = [&](int c) {
;             const size_t base = (tok0 + (size_t)c * 16) * 512 + h * 64;
; #pragma unroll
;             for (int t = 0; t < 16; ++t) { const size_t off = base + (size_t)t * 512 + j; kraw[t] = Kb[off]; araw[t] = Ab[off]; rraw[t] = Rb[off]; eraw[t] = EW[off]; }
; #pragma unroll
;             for (int q = 0; q < 4; ++q) vraw[q] = Vb[base + (size_t)(4 * fq + q) * 512 + rg * 16 + fr];
;         };
;         auto pbuild = [&](int c, LAS unsigned char* sl, LAS unsigned char* sc, int cnext) {
;             float W = 1.f;
;             const int m = j >> 5, tp = (j >> 4) & 1, jw = j & 15, pidx = (jw >> 2) * 8 + tp * 4 + (jw & 3);
; #pragma unroll
;             for (int t = 0; t < 16; ++t) {
;                 const float k = bf2f(kraw[t]), a = bf2f(araw[t]), r = bf2f(rraw[t]);
;                 const float q = k * kkc, kp1 = k * (1.f + (a - 1.f) * kac);
;                 *(LAS bf16_t*)(sc + 0 + (t * 64 + j) * 2) = bf1(q * q);
;                 *(LAS bf16_t*)(sc + 2048 + (t * 64 + j) * 2) = bf1(r * kp1 * rkc);
;             }
.Lsc_producer:
	s_sub_u32 s55, s25, 1
	s_cmp_gt_u32 s25, 4
	s_cselect_b32 s0, 1, 0
	s_sub_u32 s55, s55, s0
	v_mov_b32_e32 v22, 1.0
	v_mov_b32_e32 v23, 1.0
	v_mov_b32_e32 v24, 0xbfb8aa3b
	v_mov_b32_e32 v25, 0xbfb8aa3b
	v_mov_b32_e32 v28, 0x3f803f80
	v_mov_b32_e32 v29, 0x3f803f80
	v_mov_b32_e32 v30, 0x3f803f80
	v_mov_b32_e32 v31, 0x3f803f80
	v_cmp_eq_u32_e32 vcc, 0, v1
	s_nop 1
	v_cndmask_b32_e64 v21, 0, 1.0, vcc
	v_lshl_add_u32 v4, v2, 2, 0
	v_cmp_eq_u32_e32 vcc, v4, v1
	s_nop 1
	v_cndmask_b32_e64 v26, 0, 1.0, vcc
	v_cmp_gt_u32_e32 vcc, v4, v1
	s_nop 1
	v_cndmask_b32_e64 v34, 0, 1.0, vcc
	v_cmp_ge_u32_e32 vcc, v4, v1
	s_nop 1
	v_cndmask_b32_e64 v38, 0, 1.0, vcc
	v_lshl_add_u32 v4, v2, 2, 1
	v_cmp_eq_u32_e32 vcc, v4, v1
	s_nop 1
	v_cndmask_b32_e64 v27, 0, 1.0, vcc
	v_cmp_gt_u32_e32 vcc, v4, v1
	s_nop 1
	v_cndmask_b32_e64 v35, 0, 1.0, vcc
	v_cmp_ge_u32_e32 vcc, v4, v1
	s_nop 1
	v_cndmask_b32_e64 v39, 0, 1.0, vcc
	v_lshl_add_u32 v4, v2, 2, 2
	v_cmp_eq_u32_e32 vcc, v4, v1
	s_nop 1
	v_cndmask_b32_e64 v32, 0, 1.0, vcc
	v_cmp_gt_u32_e32 vcc, v4, v1
	s_nop 1
	v_cndmask_b32_e64 v36, 0, 1.0, vcc
	v_cmp_ge_u32_e32 vcc, v4, v1
	s_nop 1
	v_cndmask_b32_e64 v40, 0, 1.0, vcc
	v_lshl_add_u32 v4, v2, 2, 3
	v_cmp_eq_u32_e32 vcc, v4, v1
	s_nop 1
	v_cndmask_b32_e64 v33, 0, 1.0, vcc
	v_cmp_gt_u32_e32 vcc, v4, v1
	s_nop 1
	v_cndmask_b32_e64 v37, 0, 1.0, vcc
	v_cmp_ge_u32_e32 vcc, v4, v1
	s_nop 1
	v_cndmask_b32_e64 v41, 0, 1.0, vcc
	s_lshl_b32 s0, s52, 8
	v_lshl_add_u32 v4, v0, 2, s0
	v_readlane_b32 s14, v243, 51
	v_readlane_b32 s15, v243, 52
	s_nop 0
	s_lshl_b64 s[14:15], s[14:15], 2
	v_readlane_b32 s0, v252, 36
	v_readlane_b32 s1, v252, 37
	s_add_u32 s0, s0, s14
	s_addc_u32 s1, s1, s15
	global_load_dword v76, v4, s[0:1]
	v_readlane_b32 s0, v252, 38
	v_readlane_b32 s1, v252, 39
	s_add_u32 s0, s0, s14
	s_addc_u32 s1, s1, s15
	global_load_dword v80, v4, s[0:1]
	v_readlane_b32 s0, v252, 40
	v_readlane_b32 s1, v252, 41
	s_add_u32 s0, s0, s14
	s_addc_u32 s1, s1, s15
	global_load_dword v248, v4, s[0:1]
	s_mul_i32 s0, s54, 4096
	s_lshl_b32 s1, s55, 4
	s_add_u32 s1, s1, s0
	v_add_u32_e32 v8, s1, v1
	v_lshlrev_b32_e32 v8, 10, v8
	s_lshl_b32 s14, s52, 7
	v_lshl_add_u32 v4, v2, 5, s14
	v_add_u32_e32 v8, v8, v4
	v_lshl_add_u32 v9, v2, 2, s1
	v_lshlrev_b32_e32 v9, 10, v9
	s_lshl_b32 s15, s53, 5
	s_add_u32 s14, s14, s15
	v_lshl_add_u32 v4, v1, 1, s14
	v_add_u32_e32 v9, v9, v4
	v_lshlrev_b32_e32 v10, 5, v1
	v_lshrrev_b32_e32 v4, 1, v2
	v_lshlrev_b32_e32 v11, 10, v4
	v_lshl_add_u32 v11, v1, 6, v11
	v_and_b32_e32 v4, 1, v2
	v_lshl_add_u32 v11, v4, 3, v11
	v_lshlrev_b32_e32 v13, 7, v1
	v_lshl_add_u32 v13, v2, 5, v13
	v_add_u32_e32 v13, 4096, v13
	v_lshlrev_b32_e32 v16, 6, v2
	v_add_u32_e32 v16, 10752, v16
	s_mul_i32 s0, s55, 2816
	s_add_u32 s0, s0, 132096
	v_add_u32_e32 v14, s0, v7
	v_add_u32_e32 v15, s0, v6
	v_lshl_add_u32 v4, v0, 2, s0
	s_waitcnt vmcnt(0)
	ds_write_b32 v4, v76 offset:2048
	ds_write_b32 v4, v80 offset:2304
	ds_write_b32 v4, v248 offset:2560
	v_lshl_add_u32 v42, v2, 6, s0
	s_mul_i32 s57, s55, 11008
	s_mov_b32 s56, 0
	s_lshl_b32 s0, s1, 5
	s_lshl_b32 s14, s52, 2
	s_add_u32 s0, s0, s14
	s_add_u32 s0, s0, 0x9000000
	s_add_u32 s50, s74, s0
	s_addc_u32 s51, s75, 0
	s_mov_b32 s58, s55
	s_mov_b32 s42, 0
	global_load_dwordx4 v[44:47], v8, s[26:27]
	global_load_dwordx4 v[48:51], v8, s[26:27] offset:16
	global_load_dwordx4 v[52:55], v8, s[36:37]
	global_load_dwordx4 v[56:59], v8, s[36:37] offset:16
	global_load_dwordx4 v[60:63], v8, s[38:39]
	global_load_dwordx4 v[64:67], v8, s[38:39] offset:16
	global_load_dwordx4 v[68:71], v8, s[46:47]
	global_load_dwordx4 v[72:75], v8, s[46:47] offset:16
	global_load_ushort v84, v9, s[60:61] offset:0
	global_load_ushort v85, v9, s[60:61] offset:1024
	global_load_ushort v86, v9, s[60:61] offset:2048
	global_load_ushort v87, v9, s[60:61] offset:3072
	v_add_u32_e32 v8, 0x18000, v8
	v_add_u32_e32 v9, 0x18000, v9
	s_nop 1
.Lsc_p_loop:
	s_cmp_ge_u32 s58, 256
	s_cbranch_scc1 .Lsc_p_skip
	s_add_u32 s0, s57, s56
	v_add_u32_e32 v17, s0, v11
	v_add_u32_e32 v18, s0, v13
	v_add_u32_e32 v19, s0, v6
	v_add_u32_e32 v20, s0, v16
	s_waitcnt vmcnt(0)
	v_and_b32_e32 v89, 0xffff0000, v44
	v_lshlrev_b32_e32 v88, 16, v44
	v_and_b32_e32 v105, 0xffff0000, v52
	v_lshlrev_b32_e32 v104, 16, v52
	v_and_b32_e32 v121, 0xffff0000, v60
	v_lshlrev_b32_e32 v120, 16, v60
	v_cvt_f32_f16_sdwa v153, v68 dst_sel:DWORD dst_unused:UNUSED_PAD src0_sel:WORD_1
	v_cvt_f32_f16_e32 v152, v68
	v_and_b32_e32 v91, 0xffff0000, v45
	v_lshlrev_b32_e32 v90, 16, v45
	v_and_b32_e32 v107, 0xffff0000, v53
	v_lshlrev_b32_e32 v106, 16, v53
	v_and_b32_e32 v123, 0xffff0000, v61
	v_lshlrev_b32_e32 v122, 16, v61
	v_cvt_f32_f16_sdwa v155, v69 dst_sel:DWORD dst_unused:UNUSED_PAD src0_sel:WORD_1
	v_cvt_f32_f16_e32 v154, v69
	v_and_b32_e32 v93, 0xffff0000, v46
	v_lshlrev_b32_e32 v92, 16, v46
	v_and_b32_e32 v109, 0xffff0000, v54
	v_lshlrev_b32_e32 v108, 16, v54
	v_and_b32_e32 v125, 0xffff0000, v62
	v_lshlrev_b32_e32 v124, 16, v62
	v_cvt_f32_f16_sdwa v157, v70 dst_sel:DWORD dst_unused:UNUSED_PAD src0_sel:WORD_1
	v_cvt_f32_f16_e32 v156, v70
	v_and_b32_e32 v95, 0xffff0000, v47
	v_lshlrev_b32_e32 v94, 16, v47
	v_and_b32_e32 v111, 0xffff0000, v55
	v_lshlrev_b32_e32 v110, 16, v55
	v_and_b32_e32 v127, 0xffff0000, v63
	v_lshlrev_b32_e32 v126, 16, v63
	v_cvt_f32_f16_sdwa v159, v71 dst_sel:DWORD dst_unused:UNUSED_PAD src0_sel:WORD_1
	v_cvt_f32_f16_e32 v158, v71
	v_and_b32_e32 v97, 0xffff0000, v48
	v_lshlrev_b32_e32 v96, 16, v48
	v_and_b32_e32 v113, 0xffff0000, v56
	v_lshlrev_b32_e32 v112, 16, v56
	v_and_b32_e32 v129, 0xffff0000, v64
	v_lshlrev_b32_e32 v128, 16, v64
	v_cvt_f32_f16_sdwa v161, v72 dst_sel:DWORD dst_unused:UNUSED_PAD src0_sel:WORD_1
	v_cvt_f32_f16_e32 v160, v72
	v_and_b32_e32 v99, 0xffff0000, v49
	v_lshlrev_b32_e32 v98, 16, v49
	v_and_b32_e32 v115, 0xffff0000, v57
	v_lshlrev_b32_e32 v114, 16, v57
	v_and_b32_e32 v131, 0xffff0000, v65
	v_lshlrev_b32_e32 v130, 16, v65
	v_cvt_f32_f16_sdwa v163, v73 dst_sel:DWORD dst_unused:UNUSED_PAD src0_sel:WORD_1
	v_cvt_f32_f16_e32 v162, v73
	v_and_b32_e32 v101, 0xffff0000, v50
	v_lshlrev_b32_e32 v100, 16, v50
	v_and_b32_e32 v117, 0xffff0000, v58
	v_lshlrev_b32_e32 v116, 16, v58
	v_and_b32_e32 v133, 0xffff0000, v66
	v_lshlrev_b32_e32 v132, 16, v66
	v_cvt_f32_f16_sdwa v165, v74 dst_sel:DWORD dst_unused:UNUSED_PAD src0_sel:WORD_1
	v_cvt_f32_f16_e32 v164, v74
	v_and_b32_e32 v103, 0xffff0000, v51
	v_lshlrev_b32_e32 v102, 16, v51
	v_and_b32_e32 v119, 0xffff0000, v59
	v_lshlrev_b32_e32 v118, 16, v59
	v_and_b32_e32 v135, 0xffff0000, v67
	v_lshlrev_b32_e32 v134, 16, v67
	v_cvt_f32_f16_sdwa v167, v75 dst_sel:DWORD dst_unused:UNUSED_PAD src0_sel:WORD_1
	v_cvt_f32_f16_e32 v166, v75
	v_lshl_or_b32 v76, v85, 16, v84
	v_lshl_or_b32 v77, v87, 16, v86
	ds_write_b64 v19, v[76:77] offset:10240
	s_add_u32 s0, s58, 6
	s_cmp_ge_u32 s0, 256
	s_cbranch_scc1 .Lsc_p_nopf
; #define LAS __attribute__((address_space(3)))
; __device__ __forceinline__ float bf2f(bf16_t b) { return __uint_as_float(((unsigned)b) << 16); }
; __device__ __forceinline__ bf16_t bf1(float x) { return (bf16_t)(pk_bf16(x, 0.f) & 0xffffu); }
; __device__ __forceinline__ void phase_scan2(const Params& p, int l, LAS unsigned char* lds) {
;     ...
;         auto pbuild = [&](int c, LAS unsigned char* sl, LAS unsigned char* sc, int cnext) {
;             float W = 1.f;
;             const int m = j >> 5, tp = (j >> 4) & 1, jw = j & 15, pidx = (jw >> 2) * 8 + tp * 4 + (jw & 3);
; #pragma unroll
;             for (int t = 0; t < 16; ++t) {
;                 const float k = bf2f(kraw[t]), a = bf2f(araw[t]), r = bf2f(rraw[t]);
;                 const float q = k * kkc, kp1 = k * (1.f + (a - 1.f) * kac);
;                 *(LAS bf16_t*)(sc + 0 + (t * 64 + j) * 2) = bf1(q * q);
;                 *(LAS bf16_t*)(sc + 2048 + (t * 64 + j) * 2) = bf1(r * kp1 * rkc);
;             }
;     ...
;             if (cnext >= 0) pload(cnext);
	global_load_dwordx4 v[44:47], v8, s[26:27]
	global_load_dwordx4 v[48:51], v8, s[26:27] offset:16
	global_load_dwordx4 v[52:55], v8, s[36:37]
	global_load_dwordx4 v[56:59], v8, s[36:37] offset:16
	global_load_dwordx4 v[60:63], v8, s[38:39]
	global_load_dwordx4 v[64:67], v8, s[38:39] offset:16
	global_load_dwordx4 v[68:71], v8, s[46:47]
	global_load_dwordx4 v[72:75], v8, s[46:47] offset:16
	global_load_ushort v84, v9, s[60:61] offset:0
	global_load_ushort v85, v9, s[60:61] offset:1024
	global_load_ushort v86, v9, s[60:61] offset:2048
	global_load_ushort v87, v9, s[60:61] offset:3072
	v_add_u32_e32 v8, 0x18000, v8
	v_add_u32_e32 v9, 0x18000, v9
	s_nop 1
.Lsc_p_nopf:
	ds_read_b128 v[220:223], v42 offset:2304
	ds_read_b128 v[224:227], v42 offset:2320
	ds_read_b128 v[228:231], v42 offset:2048
	ds_read_b128 v[232:235], v42 offset:2064
	ds_read_b128 v[236:239], v42 offset:2560
	ds_read_b128 v[244:247], v42 offset:2576
	s_waitcnt lgkmcnt(4)
	v_add_f32_e32 v76, -1.0, v104
	v_add_f32_e32 v77, -1.0, v105
	v_pk_fma_f32 v[76:77], v[220:221], v[76:77], v[22:23]
	v_pk_mul_f32 v[136:137], v[76:77], v[88:89]
	s_waitcnt lgkmcnt(2)
	v_pk_mul_f32 v[88:89], v[228:229], v[88:89]
	v_pk_mul_f32 v[80:81], v[88:89], v[88:89]
	v_pk_mul_f32 v[248:249], v[136:137], v[120:121]
	v_cvt_pk_bf16_f32 v196, v80, v81
	s_waitcnt lgkmcnt(0)
	v_pk_mul_f32 v[248:249], v[236:237], v[248:249]
	v_cvt_pk_bf16_f32 v204, v248, v249
	v_add_f32_e32 v76, -1.0, v106
	v_add_f32_e32 v77, -1.0, v107
	v_pk_fma_f32 v[76:77], v[222:223], v[76:77], v[22:23]
	v_pk_mul_f32 v[138:139], v[76:77], v[90:91]
	v_pk_mul_f32 v[90:91], v[230:231], v[90:91]
	v_pk_mul_f32 v[80:81], v[90:91], v[90:91]
	v_pk_mul_f32 v[248:249], v[138:139], v[122:123]
	v_cvt_pk_bf16_f32 v197, v80, v81
	v_pk_mul_f32 v[248:249], v[238:239], v[248:249]
	v_cvt_pk_bf16_f32 v205, v248, v249
	s_waitcnt lgkmcnt(3)
	v_add_f32_e32 v76, -1.0, v108
	v_add_f32_e32 v77, -1.0, v109
	v_pk_fma_f32 v[76:77], v[224:225], v[76:77], v[22:23]
	v_pk_mul_f32 v[140:141], v[76:77], v[92:93]
	s_waitcnt lgkmcnt(1)
	v_pk_mul_f32 v[92:93], v[232:233], v[92:93]
	v_pk_mul_f32 v[80:81], v[92:93], v[92:93]
	v_pk_mul_f32 v[248:249], v[140:141], v[124:125]
	v_cvt_pk_bf16_f32 v198, v80, v81
	s_waitcnt lgkmcnt(0)
	v_pk_mul_f32 v[248:249], v[244:245], v[248:249]
	v_cvt_pk_bf16_f32 v206, v248, v249
	v_add_f32_e32 v76, -1.0, v110
	v_add_f32_e32 v77, -1.0, v111
	v_pk_fma_f32 v[76:77], v[226:227], v[76:77], v[22:23]
	v_pk_mul_f32 v[142:143], v[76:77], v[94:95]
	v_pk_mul_f32 v[94:95], v[234:235], v[94:95]
	v_pk_mul_f32 v[80:81], v[94:95], v[94:95]
	v_pk_mul_f32 v[248:249], v[142:143], v[126:127]
	v_cvt_pk_bf16_f32 v199, v80, v81
	v_pk_mul_f32 v[248:249], v[246:247], v[248:249]
	v_cvt_pk_bf16_f32 v207, v248, v249
	ds_read_b128 v[220:223], v42 offset:2336
	ds_read_b128 v[224:227], v42 offset:2352
	ds_read_b128 v[228:231], v42 offset:2080
	ds_read_b128 v[232:235], v42 offset:2096
	ds_read_b128 v[236:239], v42 offset:2592
	ds_read_b128 v[244:247], v42 offset:2608
	s_waitcnt lgkmcnt(4)
	v_add_f32_e32 v76, -1.0, v112
	v_add_f32_e32 v77, -1.0, v113
	v_pk_fma_f32 v[76:77], v[220:221], v[76:77], v[22:23]
	v_pk_mul_f32 v[144:145], v[76:77], v[96:97]
	s_waitcnt lgkmcnt(2)
	v_pk_mul_f32 v[96:97], v[228:229], v[96:97]
	v_pk_mul_f32 v[80:81], v[96:97], v[96:97]
	v_pk_mul_f32 v[248:249], v[144:145], v[128:129]
	v_cvt_pk_bf16_f32 v200, v80, v81
	s_waitcnt lgkmcnt(0)
	v_pk_mul_f32 v[248:249], v[236:237], v[248:249]
	v_cvt_pk_bf16_f32 v208, v248, v249
	v_add_f32_e32 v76, -1.0, v114
	v_add_f32_e32 v77, -1.0, v115
	v_pk_fma_f32 v[76:77], v[222:223], v[76:77], v[22:23]
	v_pk_mul_f32 v[146:147], v[76:77], v[98:99]
	v_pk_mul_f32 v[98:99], v[230:231], v[98:99]
	v_pk_mul_f32 v[80:81], v[98:99], v[98:99]
	v_pk_mul_f32 v[248:249], v[146:147], v[130:131]
	v_cvt_pk_bf16_f32 v201, v80, v81
	v_pk_mul_f32 v[248:249], v[238:239], v[248:249]
	v_cvt_pk_bf16_f32 v209, v248, v249
	s_waitcnt lgkmcnt(3)
	v_add_f32_e32 v76, -1.0, v116
	v_add_f32_e32 v77, -1.0, v117
	v_pk_fma_f32 v[76:77], v[224:225], v[76:77], v[22:23]
	v_pk_mul_f32 v[148:149], v[76:77], v[100:101]
	s_waitcnt lgkmcnt(1)
	v_pk_mul_f32 v[100:101], v[232:233], v[100:101]
	v_pk_mul_f32 v[80:81], v[100:101], v[100:101]
	v_pk_mul_f32 v[248:249], v[148:149], v[132:133]
	v_cvt_pk_bf16_f32 v202, v80, v81
	s_waitcnt lgkmcnt(0)
; #define LAS __attribute__((address_space(3)))
; __device__ __forceinline__ float bf2f(bf16_t b) { return __uint_as_float(((unsigned)b) << 16); }
; __device__ __forceinline__ void phase_scan2(const Params& p, int l, LAS unsigned char* lds) {
;     ...
;             { const bf16x8 ones = __builtin_bit_cast(bf16x8, (u32x4){0x3F803F80u, 0x3F803F80u, 0x3F803F80u, 0x3F803F80u});
;               f32x4 sq = (f32x4){0.f, 0.f, 0.f, 0.f}, sb = sq;
; #pragma unroll
;               for (int kk2 = 0; kk2 < 2; ++kk2) {
;                   const bf16x8 fa = *(LAS const bf16x8*)(sc + 0 + (fr * 64 + kk2 * 32 + fq * 8) * 2), fu = *(LAS const bf16x8*)(sc + 2048 + (fr * 64 + kk2 * 32 + fq * 8) * 2);
;                   sq = __builtin_amdgcn_mfma_f32_16x16x32_bf16(fa, ones, sq, 0, 0, 0); sb = __builtin_amdgcn_mfma_f32_16x16x32_bf16(fu, ones, sb, 0, 0, 0);
;               }
;               if (fr == 0) { *(LAS f32x4*)(sl + SC_X + fq * 16) = sq; *(LAS f32x4*)(sl + SC_X + 64 + fq * 16) = sb; }
;               asm volatile("s_waitcnt lgkmcnt(0)" ::: "memory");
;               if (rg == 0 && lane < 16) CB[(tok0 + (size_t)c * 16 + lane) * 8 + h] = *(LAS const float*)(sl + SC_X + 64 + lane * 4);
;               asm volatile("s_waitcnt lgkmcnt(0)" ::: "memory");
;             }
; #pragma unroll
;             for (int t = 0; t < 16; ++t) {
;                 const float k = bf2f(kraw[t]), a = bf2f(araw[t]), r = bf2f(rraw[t]), ew = (float)eraw[t];
;                 const float kk = k * kkc * rsqrtf(fmaxf(*(LAS const float*)(sl + SC_X + t * 4), 1e-24f));
;                 const float kp = k * (1.f + (a - 1.f) * kac);
;                 const float at = -kk * W;
;                 W *= __expf(-ew);
;                 const float rt = r * W, iw = __builtin_amdgcn_rcpf(W);
	v_pk_mul_f32 v[248:249], v[244:245], v[248:249]
	v_cvt_pk_bf16_f32 v210, v248, v249
	v_add_f32_e32 v76, -1.0, v118
	v_add_f32_e32 v77, -1.0, v119
	v_pk_fma_f32 v[76:77], v[226:227], v[76:77], v[22:23]
	v_pk_mul_f32 v[150:151], v[76:77], v[102:103]
	v_pk_mul_f32 v[102:103], v[234:235], v[102:103]
	v_pk_mul_f32 v[80:81], v[102:103], v[102:103]
	v_pk_mul_f32 v[248:249], v[150:151], v[134:135]
	v_cvt_pk_bf16_f32 v203, v80, v81
	v_pk_mul_f32 v[248:249], v[246:247], v[248:249]
	v_cvt_pk_bf16_f32 v211, v248, v249
	v_mfma_f32_16x16x32_bf16 v[168:171], v[28:31], v[196:199], 0
	v_mfma_f32_16x16x32_bf16 v[172:175], v[28:31], v[204:207], 0
	v_mfma_f32_16x16x32_bf16 v[168:171], v[28:31], v[200:203], v[168:171]
	v_mfma_f32_16x16x32_bf16 v[172:175], v[28:31], v[208:211], v[172:175]
	v_pk_mul_f32 v[152:153], v[152:153], v[24:25]
	v_pk_mul_f32 v[154:155], v[154:155], v[24:25]
	v_pk_mul_f32 v[156:157], v[156:157], v[24:25]
	v_pk_mul_f32 v[158:159], v[158:159], v[24:25]
	v_pk_mul_f32 v[160:161], v[160:161], v[24:25]
	v_pk_mul_f32 v[162:163], v[162:163], v[24:25]
	v_pk_mul_f32 v[164:165], v[164:165], v[24:25]
	v_pk_mul_f32 v[166:167], v[166:167], v[24:25]
	v_add_f32_dpp v152, v152, v152 row_shr:1 row_mask:0xf bank_mask:0xf bound_ctrl:1
	v_add_f32_dpp v153, v153, v153 row_shr:1 row_mask:0xf bank_mask:0xf bound_ctrl:1
	v_add_f32_dpp v154, v154, v154 row_shr:1 row_mask:0xf bank_mask:0xf bound_ctrl:1
	v_add_f32_dpp v155, v155, v155 row_shr:1 row_mask:0xf bank_mask:0xf bound_ctrl:1
	v_add_f32_dpp v156, v156, v156 row_shr:1 row_mask:0xf bank_mask:0xf bound_ctrl:1
	v_add_f32_dpp v157, v157, v157 row_shr:1 row_mask:0xf bank_mask:0xf bound_ctrl:1
	v_add_f32_dpp v158, v158, v158 row_shr:1 row_mask:0xf bank_mask:0xf bound_ctrl:1
	v_add_f32_dpp v159, v159, v159 row_shr:1 row_mask:0xf bank_mask:0xf bound_ctrl:1
	v_add_f32_dpp v160, v160, v160 row_shr:1 row_mask:0xf bank_mask:0xf bound_ctrl:1
	v_add_f32_dpp v161, v161, v161 row_shr:1 row_mask:0xf bank_mask:0xf bound_ctrl:1
	v_add_f32_dpp v162, v162, v162 row_shr:1 row_mask:0xf bank_mask:0xf bound_ctrl:1
	v_add_f32_dpp v163, v163, v163 row_shr:1 row_mask:0xf bank_mask:0xf bound_ctrl:1
	v_add_f32_dpp v164, v164, v164 row_shr:1 row_mask:0xf bank_mask:0xf bound_ctrl:1
	v_add_f32_dpp v165, v165, v165 row_shr:1 row_mask:0xf bank_mask:0xf bound_ctrl:1
	v_add_f32_dpp v166, v166, v166 row_shr:1 row_mask:0xf bank_mask:0xf bound_ctrl:1
	v_add_f32_dpp v167, v167, v167 row_shr:1 row_mask:0xf bank_mask:0xf bound_ctrl:1
	v_add_f32_dpp v152, v152, v152 row_shr:2 row_mask:0xf bank_mask:0xf bound_ctrl:1
	v_add_f32_dpp v153, v153, v153 row_shr:2 row_mask:0xf bank_mask:0xf bound_ctrl:1
	v_add_f32_dpp v154, v154, v154 row_shr:2 row_mask:0xf bank_mask:0xf bound_ctrl:1
	v_add_f32_dpp v155, v155, v155 row_shr:2 row_mask:0xf bank_mask:0xf bound_ctrl:1
	v_add_f32_dpp v156, v156, v156 row_shr:2 row_mask:0xf bank_mask:0xf bound_ctrl:1
	v_add_f32_dpp v157, v157, v157 row_shr:2 row_mask:0xf bank_mask:0xf bound_ctrl:1
	v_add_f32_dpp v158, v158, v158 row_shr:2 row_mask:0xf bank_mask:0xf bound_ctrl:1
	v_add_f32_dpp v159, v159, v159 row_shr:2 row_mask:0xf bank_mask:0xf bound_ctrl:1
	v_add_f32_dpp v160, v160, v160 row_shr:2 row_mask:0xf bank_mask:0xf bound_ctrl:1
	v_add_f32_dpp v161, v161, v161 row_shr:2 row_mask:0xf bank_mask:0xf bound_ctrl:1
	v_add_f32_dpp v162, v162, v162 row_shr:2 row_mask:0xf bank_mask:0xf bound_ctrl:1
	v_add_f32_dpp v163, v163, v163 row_shr:2 row_mask:0xf bank_mask:0xf bound_ctrl:1
	v_add_f32_dpp v164, v164, v164 row_shr:2 row_mask:0xf bank_mask:0xf bound_ctrl:1
	v_add_f32_dpp v165, v165, v165 row_shr:2 row_mask:0xf bank_mask:0xf bound_ctrl:1
	v_add_f32_dpp v166, v166, v166 row_shr:2 row_mask:0xf bank_mask:0xf bound_ctrl:1
	v_add_f32_dpp v167, v167, v167 row_shr:2 row_mask:0xf bank_mask:0xf bound_ctrl:1
	v_add_f32_dpp v152, v152, v152 row_shr:4 row_mask:0xf bank_mask:0xf bound_ctrl:1
	v_add_f32_dpp v153, v153, v153 row_shr:4 row_mask:0xf bank_mask:0xf bound_ctrl:1
	v_add_f32_dpp v154, v154, v154 row_shr:4 row_mask:0xf bank_mask:0xf bound_ctrl:1
	v_add_f32_dpp v155, v155, v155 row_shr:4 row_mask:0xf bank_mask:0xf bound_ctrl:1
	v_add_f32_dpp v156, v156, v156 row_shr:4 row_mask:0xf bank_mask:0xf bound_ctrl:1
	v_add_f32_dpp v157, v157, v157 row_shr:4 row_mask:0xf bank_mask:0xf bound_ctrl:1
	v_add_f32_dpp v158, v158, v158 row_shr:4 row_mask:0xf bank_mask:0xf bound_ctrl:1
	v_add_f32_dpp v159, v159, v159 row_shr:4 row_mask:0xf bank_mask:0xf bound_ctrl:1
	v_add_f32_dpp v160, v160, v160 row_shr:4 row_mask:0xf bank_mask:0xf bound_ctrl:1
	v_add_f32_dpp v161, v161, v161 row_shr:4 row_mask:0xf bank_mask:0xf bound_ctrl:1
	v_add_f32_dpp v162, v162, v162 row_shr:4 row_mask:0xf bank_mask:0xf bound_ctrl:1
	v_add_f32_dpp v163, v163, v163 row_shr:4 row_mask:0xf bank_mask:0xf bound_ctrl:1
	v_add_f32_dpp v164, v164, v164 row_shr:4 row_mask:0xf bank_mask:0xf bound_ctrl:1
	v_add_f32_dpp v165, v165, v165 row_shr:4 row_mask:0xf bank_mask:0xf bound_ctrl:1
	v_add_f32_dpp v166, v166, v166 row_shr:4 row_mask:0xf bank_mask:0xf bound_ctrl:1
	v_add_f32_dpp v167, v167, v167 row_shr:4 row_mask:0xf bank_mask:0xf bound_ctrl:1
	v_add_f32_dpp v152, v152, v152 row_shr:8 row_mask:0xf bank_mask:0xf bound_ctrl:1
	v_add_f32_dpp v153, v153, v153 row_shr:8 row_mask:0xf bank_mask:0xf bound_ctrl:1
	v_add_f32_dpp v154, v154, v154 row_shr:8 row_mask:0xf bank_mask:0xf bound_ctrl:1
	v_add_f32_dpp v155, v155, v155 row_shr:8 row_mask:0xf bank_mask:0xf bound_ctrl:1
	v_add_f32_dpp v156, v156, v156 row_shr:8 row_mask:0xf bank_mask:0xf bound_ctrl:1
	v_add_f32_dpp v157, v157, v157 row_shr:8 row_mask:0xf bank_mask:0xf bound_ctrl:1
	v_add_f32_dpp v158, v158, v158 row_shr:8 row_mask:0xf bank_mask:0xf bound_ctrl:1
; #define LAS __attribute__((address_space(3)))
; __device__ __forceinline__ unsigned pk_bf16(float lo, float hi) { const f32x2_t f = {lo, hi}; return __builtin_bit_cast(unsigned, __builtin_convertvector(f, bf16x2_t)); }
; __device__ __forceinline__ float bf2f(bf16_t b) { return __uint_as_float(((unsigned)b) << 16); }
; __device__ __forceinline__ void phase_scan2(const Params& p, int l, LAS unsigned char* lds) {
;     ...
;               if (fr == 0) { *(LAS f32x4*)(sl + SC_X + fq * 16) = sq; *(LAS f32x4*)(sl + SC_X + 64 + fq * 16) = sb; }
;               asm volatile("s_waitcnt lgkmcnt(0)" ::: "memory");
;               if (rg == 0 && lane < 16) CB[(tok0 + (size_t)c * 16 + lane) * 8 + h] = *(LAS const float*)(sl + SC_X + 64 + lane * 4);
;               asm volatile("s_waitcnt lgkmcnt(0)" ::: "memory");
;             }
; #pragma unroll
;             for (int t = 0; t < 16; ++t) {
;                 const float k = bf2f(kraw[t]), a = bf2f(araw[t]), r = bf2f(rraw[t]), ew = (float)eraw[t];
;                 const float kk = k * kkc * rsqrtf(fmaxf(*(LAS const float*)(sl + SC_X + t * 4), 1e-24f));
;                 const float kp = k * (1.f + (a - 1.f) * kac);
;                 const float at = -kk * W;
;                 W *= __expf(-ew);
;                 const float rt = r * W, iw = __builtin_amdgcn_rcpf(W);
;                 const unsigned wbk = pk_bf16(kk * a * iw, kp * iw), war = pk_bf16(at, rt);
;                 const bf16_t bh = (bf16_t)(wbk & 0xffffu), kh = (bf16_t)(wbk >> 16), ah = (bf16_t)(war & 0xffffu), rh = (bf16_t)(war >> 16);
;                 *(LAS bf16_t*)(sl + SC_AT + ((m * 16 + t) * 32 + pidx) * 2) = ah;
;                 *(LAS bf16_t*)(sl + SC_RT + ((m * 16 + t) * 32 + pidx) * 2) = rh;
;                 *(LAS bf16_t*)(sl + SC_BBT + (j * SC_BS + t) * 2) = bh;
;                 *(LAS bf16_t*)(sl + SC_KBT + (j * SC_BS + t) * 2) = kh;
;                 *(LAS bf16_t*)(sc + 0 + ((m * 16 + t) * 32 + pidx) * 2) = bh;
;                 *(LAS bf16_t*)(sc + 2048 + ((m * 16 + t) * 32 + pidx) * 2) = kh;
;             }
	v_add_f32_dpp v159, v159, v159 row_shr:8 row_mask:0xf bank_mask:0xf bound_ctrl:1
	v_add_f32_dpp v160, v160, v160 row_shr:8 row_mask:0xf bank_mask:0xf bound_ctrl:1
	v_add_f32_dpp v161, v161, v161 row_shr:8 row_mask:0xf bank_mask:0xf bound_ctrl:1
	v_add_f32_dpp v162, v162, v162 row_shr:8 row_mask:0xf bank_mask:0xf bound_ctrl:1
	v_add_f32_dpp v163, v163, v163 row_shr:8 row_mask:0xf bank_mask:0xf bound_ctrl:1
	v_add_f32_dpp v164, v164, v164 row_shr:8 row_mask:0xf bank_mask:0xf bound_ctrl:1
	v_add_f32_dpp v165, v165, v165 row_shr:8 row_mask:0xf bank_mask:0xf bound_ctrl:1
	v_add_f32_dpp v166, v166, v166 row_shr:8 row_mask:0xf bank_mask:0xf bound_ctrl:1
	v_add_f32_dpp v167, v167, v167 row_shr:8 row_mask:0xf bank_mask:0xf bound_ctrl:1
	v_exp_f32_e32 v196, v152
	v_exp_f32_e32 v197, v153
	v_exp_f32_e32 v198, v154
	v_exp_f32_e32 v199, v155
	v_exp_f32_e32 v200, v156
	v_exp_f32_e32 v201, v157
	v_exp_f32_e32 v202, v158
	v_exp_f32_e32 v203, v159
	v_exp_f32_e32 v204, v160
	v_exp_f32_e32 v205, v161
	v_exp_f32_e32 v206, v162
	v_exp_f32_e32 v207, v163
	v_exp_f32_e32 v208, v164
	v_exp_f32_e32 v209, v165
	v_exp_f32_e32 v210, v166
	v_exp_f32_e32 v211, v167
	v_max_f32_e32 v176, 0x179abe15, v168
	v_rsq_f32_e32 v176, v176
	v_exp_f32_e64 v152, -v152
	v_exp_f32_e64 v153, -v153
	v_exp_f32_e64 v154, -v154
	v_exp_f32_e64 v155, -v155
	v_exp_f32_e64 v156, -v156
	v_exp_f32_e64 v157, -v157
	v_exp_f32_e64 v158, -v158
	v_exp_f32_e64 v159, -v159
	v_exp_f32_e64 v160, -v160
	v_exp_f32_e64 v161, -v161
	v_exp_f32_e64 v162, -v162
	v_exp_f32_e64 v163, -v163
	v_exp_f32_e64 v164, -v164
	v_exp_f32_e64 v165, -v165
	v_exp_f32_e64 v166, -v166
	v_exp_f32_e64 v167, -v167
	s_cmp_lg_u32 s53, 0
	s_nop 0
	s_cbranch_scc1 .Lsc_p_nocb
	s_mov_b64 exec, 0xffff
	global_store_dword v10, v172, s[50:51]
	s_mov_b64 exec, -1
.Lsc_p_nocb:
	v_pk_mul_f32 v[88:89], v[88:89], v[176:177] op_sel_hi:[1,0]
	v_mov_b32_dpp v76, v196 row_shr:1 row_mask:0xf bank_mask:0xf bound_ctrl:1
	v_mov_b32_dpp v77, v197 row_shr:1 row_mask:0xf bank_mask:0xf bound_ctrl:1
	v_pk_mul_f32 v[80:81], v[120:121], v[196:197]
	v_pk_mul_f32 v[104:105], v[88:89], v[104:105]
	v_max_f32_e32 v76, v76, v21
	v_max_f32_e32 v77, v77, v21
	v_pk_mul_f32 v[248:249], v[104:105], v[152:153]
	v_pk_mul_f32 v[250:251], v[136:137], v[152:153]
	v_pk_mul_f32 v[76:77], v[88:89], v[76:77] neg_lo:[1,0] neg_hi:[1,0]
	v_cvt_pk_bf16_f32 v220, v80, v81
	v_cvt_pk_bf16_f32 v228, v248, v249
	v_cvt_pk_bf16_f32 v236, v250, v251
	v_cvt_pk_bf16_f32 v168, v76, v77
	v_pk_mul_f32 v[90:91], v[90:91], v[176:177] op_sel_hi:[1,0]
	v_mov_b32_dpp v76, v198 row_shr:1 row_mask:0xf bank_mask:0xf bound_ctrl:1
	v_mov_b32_dpp v77, v199 row_shr:1 row_mask:0xf bank_mask:0xf bound_ctrl:1
	v_pk_mul_f32 v[80:81], v[122:123], v[198:199]
	v_pk_mul_f32 v[106:107], v[90:91], v[106:107]
	v_max_f32_e32 v76, v76, v21
	v_max_f32_e32 v77, v77, v21
	v_pk_mul_f32 v[248:249], v[106:107], v[154:155]
	v_pk_mul_f32 v[250:251], v[138:139], v[154:155]
	v_pk_mul_f32 v[76:77], v[90:91], v[76:77] neg_lo:[1,0] neg_hi:[1,0]
	v_cvt_pk_bf16_f32 v221, v80, v81
	v_cvt_pk_bf16_f32 v229, v248, v249
	v_cvt_pk_bf16_f32 v237, v250, v251
	v_cvt_pk_bf16_f32 v169, v76, v77
	v_pk_mul_f32 v[92:93], v[92:93], v[176:177] op_sel_hi:[1,0]
	v_mov_b32_dpp v76, v200 row_shr:1 row_mask:0xf bank_mask:0xf bound_ctrl:1
	v_mov_b32_dpp v77, v201 row_shr:1 row_mask:0xf bank_mask:0xf bound_ctrl:1
	v_pk_mul_f32 v[80:81], v[124:125], v[200:201]
	v_pk_mul_f32 v[108:109], v[92:93], v[108:109]
	v_max_f32_e32 v76, v76, v21
	v_max_f32_e32 v77, v77, v21
	v_pk_mul_f32 v[248:249], v[108:109], v[156:157]
	v_pk_mul_f32 v[250:251], v[140:141], v[156:157]
	v_pk_mul_f32 v[76:77], v[92:93], v[76:77] neg_lo:[1,0] neg_hi:[1,0]
	v_cvt_pk_bf16_f32 v222, v80, v81
	v_cvt_pk_bf16_f32 v230, v248, v249
	v_cvt_pk_bf16_f32 v238, v250, v251
	v_cvt_pk_bf16_f32 v170, v76, v77
	v_pk_mul_f32 v[94:95], v[94:95], v[176:177] op_sel_hi:[1,0]
	v_mov_b32_dpp v76, v202 row_shr:1 row_mask:0xf bank_mask:0xf bound_ctrl:1
	v_mov_b32_dpp v77, v203 row_shr:1 row_mask:0xf bank_mask:0xf bound_ctrl:1
	v_pk_mul_f32 v[80:81], v[126:127], v[202:203]
	v_pk_mul_f32 v[110:111], v[94:95], v[110:111]
	v_max_f32_e32 v76, v76, v21
	v_max_f32_e32 v77, v77, v21
	v_pk_mul_f32 v[248:249], v[110:111], v[158:159]
	v_pk_mul_f32 v[250:251], v[142:143], v[158:159]
	v_pk_mul_f32 v[76:77], v[94:95], v[76:77] neg_lo:[1,0] neg_hi:[1,0]
	v_cvt_pk_bf16_f32 v223, v80, v81
	v_cvt_pk_bf16_f32 v231, v248, v249
	v_cvt_pk_bf16_f32 v239, v250, v251
	v_cvt_pk_bf16_f32 v171, v76, v77
	v_pk_mul_f32 v[96:97], v[96:97], v[176:177] op_sel_hi:[1,0]
	v_mov_b32_dpp v76, v204 row_shr:1 row_mask:0xf bank_mask:0xf bound_ctrl:1
	v_mov_b32_dpp v77, v205 row_shr:1 row_mask:0xf bank_mask:0xf bound_ctrl:1
	v_pk_mul_f32 v[80:81], v[128:129], v[204:205]
	v_pk_mul_f32 v[112:113], v[96:97], v[112:113]
	v_max_f32_e32 v76, v76, v21
	v_max_f32_e32 v77, v77, v21
	v_pk_mul_f32 v[248:249], v[112:113], v[160:161]
	v_pk_mul_f32 v[250:251], v[144:145], v[160:161]
	v_pk_mul_f32 v[76:77], v[96:97], v[76:77] neg_lo:[1,0] neg_hi:[1,0]
	v_cvt_pk_bf16_f32 v224, v80, v81
	v_cvt_pk_bf16_f32 v232, v248, v249
	v_cvt_pk_bf16_f32 v244, v250, v251
	v_cvt_pk_bf16_f32 v172, v76, v77
	v_pk_mul_f32 v[98:99], v[98:99], v[176:177] op_sel_hi:[1,0]
	v_mov_b32_dpp v76, v206 row_shr:1 row_mask:0xf bank_mask:0xf bound_ctrl:1
	v_mov_b32_dpp v77, v207 row_shr:1 row_mask:0xf bank_mask:0xf bound_ctrl:1
	v_pk_mul_f32 v[80:81], v[130:131], v[206:207]
	v_pk_mul_f32 v[114:115], v[98:99], v[114:115]
	v_max_f32_e32 v76, v76, v21
	v_max_f32_e32 v77, v77, v21
	v_pk_mul_f32 v[248:249], v[114:115], v[162:163]
	v_pk_mul_f32 v[250:251], v[146:147], v[162:163]
; __device__ __forceinline__ void phase_scan2(const Params& p, int l, LAS unsigned char* lds) {
;     ...
;                 const unsigned wbk = pk_bf16(kk * a * iw, kp * iw), war = pk_bf16(at, rt);
;                 const bf16_t bh = (bf16_t)(wbk & 0xffffu), kh = (bf16_t)(wbk >> 16), ah = (bf16_t)(war & 0xffffu), rh = (bf16_t)(war >> 16);
;                 *(LAS bf16_t*)(sl + SC_AT + ((m * 16 + t) * 32 + pidx) * 2) = ah;
;                 *(LAS bf16_t*)(sl + SC_RT + ((m * 16 + t) * 32 + pidx) * 2) = rh;
;                 *(LAS bf16_t*)(sl + SC_BBT + (j * SC_BS + t) * 2) = bh;
;                 *(LAS bf16_t*)(sl + SC_KBT + (j * SC_BS + t) * 2) = kh;
;                 *(LAS bf16_t*)(sc + 0 + ((m * 16 + t) * 32 + pidx) * 2) = bh;
;                 *(LAS bf16_t*)(sc + 2048 + ((m * 16 + t) * 32 + pidx) * 2) = kh;
;             }
;             *(LAS float*)(sl + SC_WC + j * 4) = W;
; #pragma unroll
;             for (int q = 0; q < 4; ++q) *(LAS bf16_t*)(sl + SC_VP + (fr * 16 + 4 * fq + q) * 2) = vraw[q];
;             if (cnext >= 0) pload(cnext);
;             asm volatile("s_waitcnt lgkmcnt(0)" ::: "memory");
;             f32x4 AB = (f32x4){0.f, 0.f, 0.f, 0.f}, AKm = AB, RBm = AB, RKm = AB;
; #pragma unroll
;             for (int kk2 = 0; kk2 < 2; ++kk2) {
;                 const int fo = ((kk2 * 16 + fr) * 32 + fq * 8) * 2;
;                 const bf16x8 fa = *(LAS const bf16x8*)(sl + SC_AT + fo), fr_ = *(LAS const bf16x8*)(sl + SC_RT + fo);
;                 const bf16x8 fb = *(LAS const bf16x8*)(sc + 0 + fo), fk = *(LAS const bf16x8*)(sc + 2048 + fo);
;                 AB = __builtin_amdgcn_mfma_f32_16x16x32_bf16(fa, fb, AB, 0, 0, 0); AKm = __builtin_amdgcn_mfma_f32_16x16x32_bf16(fa, fk, AKm, 0, 0, 0);
;                 RBm = __builtin_amdgcn_mfma_f32_16x16x32_bf16(fr_, fb, RBm, 0, 0, 0); RKm = __builtin_amdgcn_mfma_f32_16x16x32_bf16(fr_, fk, RKm, 0, 0, 0);
;             }
; #pragma unroll
;             for (int r = 0; r < 4; ++r) { const int t = 4 * fq + r; const bool lo = fr < t, le = fr <= t;
;                 AB[r] = lo ? AB[r] : 0.f; AKm[r] = lo ? AKm[r] : 0.f; RBm[r] = le ? RBm[r] : 0.f; RKm[r] = le ? RKm[r] : 0.f; }
;             asm volatile("s_waitcnt lgkmcnt(0)" ::: "memory");
;             st_mat(sl + SC_AK, nullptr, nullptr, nullptr, AKm, fr, fq);
;             st_mat(sl + SC_RB, nullptr, nullptr, nullptr, RBm, fr, fq);
	v_pk_mul_f32 v[76:77], v[98:99], v[76:77] neg_lo:[1,0] neg_hi:[1,0]
	v_cvt_pk_bf16_f32 v225, v80, v81
	v_cvt_pk_bf16_f32 v233, v248, v249
	v_cvt_pk_bf16_f32 v245, v250, v251
	v_cvt_pk_bf16_f32 v173, v76, v77
	v_pk_mul_f32 v[100:101], v[100:101], v[176:177] op_sel_hi:[1,0]
	v_mov_b32_dpp v76, v208 row_shr:1 row_mask:0xf bank_mask:0xf bound_ctrl:1
	v_mov_b32_dpp v77, v209 row_shr:1 row_mask:0xf bank_mask:0xf bound_ctrl:1
	v_pk_mul_f32 v[80:81], v[132:133], v[208:209]
	v_pk_mul_f32 v[116:117], v[100:101], v[116:117]
	v_max_f32_e32 v76, v76, v21
	v_max_f32_e32 v77, v77, v21
	v_pk_mul_f32 v[248:249], v[116:117], v[164:165]
	v_pk_mul_f32 v[250:251], v[148:149], v[164:165]
	v_pk_mul_f32 v[76:77], v[100:101], v[76:77] neg_lo:[1,0] neg_hi:[1,0]
	v_cvt_pk_bf16_f32 v226, v80, v81
	v_cvt_pk_bf16_f32 v234, v248, v249
	v_cvt_pk_bf16_f32 v246, v250, v251
	v_cvt_pk_bf16_f32 v174, v76, v77
	v_pk_mul_f32 v[102:103], v[102:103], v[176:177] op_sel_hi:[1,0]
	v_mov_b32_dpp v76, v210 row_shr:1 row_mask:0xf bank_mask:0xf bound_ctrl:1
	v_mov_b32_dpp v77, v211 row_shr:1 row_mask:0xf bank_mask:0xf bound_ctrl:1
	v_pk_mul_f32 v[80:81], v[134:135], v[210:211]
	v_pk_mul_f32 v[118:119], v[102:103], v[118:119]
	v_max_f32_e32 v76, v76, v21
	v_max_f32_e32 v77, v77, v21
	v_pk_mul_f32 v[248:249], v[118:119], v[166:167]
	v_pk_mul_f32 v[250:251], v[150:151], v[166:167]
	v_pk_mul_f32 v[76:77], v[102:103], v[76:77] neg_lo:[1,0] neg_hi:[1,0]
	v_cvt_pk_bf16_f32 v227, v80, v81
	v_cvt_pk_bf16_f32 v235, v248, v249
	v_cvt_pk_bf16_f32 v247, v250, v251
	v_cvt_pk_bf16_f32 v175, v76, v77
	ds_write_b128 v18, v[228:231] offset:0
	ds_write_b128 v18, v[236:239] offset:2048
	ds_write_b128 v18, v[232:235] offset:16
	ds_write_b128 v18, v[244:247] offset:2064
	ds_write_b64 v17, v[168:169] offset:0
	ds_write_b64 v17, v[220:221] offset:2048
	ds_write_b64 v17, v[170:171] offset:16
	ds_write_b64 v17, v[222:223] offset:2064
	ds_write_b64 v17, v[172:173] offset:32
	ds_write_b64 v17, v[224:225] offset:2080
	ds_write_b64 v17, v[174:175] offset:48
	ds_write_b64 v17, v[226:227] offset:2096
	s_mov_b32 exec_lo, 0x80008000
	s_mov_b32 exec_hi, 0x80008000
	ds_write_b128 v20, v[196:199] offset:0
	ds_write_b128 v20, v[200:203] offset:16
	ds_write_b128 v20, v[204:207] offset:32
	ds_write_b128 v20, v[208:211] offset:48
	s_mov_b64 exec, -1
	v_mfma_f32_16x16x32_bf16 v[88:91], v[168:171], v[228:231], 0
	v_mfma_f32_16x16x32_bf16 v[92:95], v[168:171], v[236:239], 0
	v_mfma_f32_16x16x32_bf16 v[96:99], v[220:223], v[228:231], 0
	v_mfma_f32_16x16x32_bf16 v[100:103], v[220:223], v[236:239], 0
	v_mfma_f32_16x16x32_bf16 v[88:91], v[172:175], v[232:235], v[88:91]
	v_mfma_f32_16x16x32_bf16 v[92:95], v[172:175], v[244:247], v[92:95]
	v_mfma_f32_16x16x32_bf16 v[96:99], v[224:227], v[232:235], v[96:99]
	v_mfma_f32_16x16x32_bf16 v[100:103], v[224:227], v[244:247], v[100:103]
	s_nop 4
	v_mul_f32_e32 v88, v34, v88
	v_mul_f32_e32 v89, v35, v89
	v_mul_f32_e32 v90, v36, v90
	v_mul_f32_e32 v91, v37, v91
	v_mul_f32_e32 v92, v34, v92
	v_mul_f32_e32 v93, v35, v93
	v_mul_f32_e32 v94, v36, v94
	v_mul_f32_e32 v95, v37, v95
	v_mul_f32_e32 v96, v38, v96
	v_mul_f32_e32 v97, v39, v97
	v_mul_f32_e32 v98, v40, v98
	v_mul_f32_e32 v99, v41, v99
	v_mul_f32_e32 v100, v38, v100
	v_mul_f32_e32 v101, v39, v101
	v_mul_f32_e32 v102, v40, v102
	v_mul_f32_e32 v103, v41, v103
	v_cvt_pk_bf16_f32 v76, v92, v93
	v_cvt_pk_bf16_f32 v77, v94, v95
	ds_write_b64 v19, v[76:77] offset:8192
	v_cvt_pk_bf16_f32 v76, v96, v97
	v_cvt_pk_bf16_f32 v77, v98, v99
	ds_write_b64 v19, v[76:77] offset:9216
	v_cvt_pk_bf16_f32 v76, v100, v101
	v_cvt_pk_bf16_f32 v77, v102, v103
	ds_write_b64 v19, v[76:77] offset:9728
	v_cvt_pk_bf16_f32 v76, v88, v89
	v_cvt_pk_bf16_f32 v77, v90, v91
	ds_write_b64 v15, v[76:77] offset:0
	v_add_f32_e32 v248, v26, v88
	v_add_f32_e32 v249, v27, v89
	v_add_f32_e32 v250, v32, v90
	v_add_f32_e32 v251, v33, v91
	v_cvt_pk_bf16_f32 v80, v248, v249
	v_cvt_pk_bf16_f32 v81, v250, v251
	ds_write_b64 v15, v[80:81] offset:512
	s_waitcnt lgkmcnt(0)
	ds_read_b64_tr_b16 v[112:113], v14 offset:0
	ds_read_b64 v[114:115], v15 offset:0
	s_waitcnt lgkmcnt(0)
	v_mfma_f32_16x16x16_bf16 v[104:107], v[112:113], v[114:115], 0
	s_nop 7
	v_cvt_pk_bf16_f32 v76, v104, v105
	v_cvt_pk_bf16_f32 v77, v106, v107
	ds_write_b64 v15, v[76:77] offset:1024
	v_add_f32_e32 v248, v26, v104
	v_add_f32_e32 v249, v27, v105
	v_add_f32_e32 v250, v32, v106
	v_add_f32_e32 v251, v33, v107
	v_cvt_pk_bf16_f32 v80, v248, v249
	v_cvt_pk_bf16_f32 v81, v250, v251
	ds_write_b64 v15, v[80:81] offset:1536
	s_waitcnt lgkmcnt(0)
	ds_read_b64_tr_b16 v[112:113], v14 offset:1024
	ds_read_b64 v[114:115], v15 offset:1024
	ds_read_b64_tr_b16 v[116:117], v14 offset:512
	ds_read_b64 v[118:119], v15 offset:1536
	s_waitcnt lgkmcnt(2)
	v_mfma_f32_16x16x16_bf16 v[104:107], v[112:113], v[114:115], 0
	s_waitcnt lgkmcnt(0)
	v_mfma_f32_16x16x16_bf16 v[108:111], v[116:117], v[118:119], 0
	s_nop 5
	v_cvt_pk_bf16_f32 v76, v104, v105
	v_cvt_pk_bf16_f32 v77, v106, v107
	ds_write_b64 v15, v[76:77] offset:0
	v_add_f32_e32 v248, v26, v104
	v_add_f32_e32 v249, v27, v105
	v_add_f32_e32 v250, v32, v106
	v_add_f32_e32 v251, v33, v107
	v_cvt_pk_bf16_f32 v80, v248, v249
	v_cvt_pk_bf16_f32 v81, v250, v251
	ds_write_b64 v15, v[80:81] offset:512
	v_cvt_pk_bf16_f32 v76, v108, v109
	v_cvt_pk_bf16_f32 v77, v110, v111
	ds_write_b64 v15, v[76:77] offset:1024
	s_waitcnt lgkmcnt(0)
	ds_read_b64_tr_b16 v[112:113], v14 offset:0
	ds_read_b64 v[114:115], v15 offset:0
	ds_read_b64_tr_b16 v[116:117], v14 offset:1024
	ds_read_b64 v[118:119], v15 offset:512
	s_waitcnt lgkmcnt(2)
	v_mfma_f32_16x16x16_bf16 v[104:107], v[112:113], v[114:115], 0
	s_waitcnt lgkmcnt(0)
	v_mfma_f32_16x16x16_bf16 v[108:111], v[116:117], v[118:119], 0
	s_nop 5
	v_add_f32_e32 v248, v26, v104
	v_add_f32_e32 v249, v27, v105
	v_add_f32_e32 v250, v32, v106
	v_add_f32_e32 v251, v33, v107
	v_cvt_pk_bf16_f32 v80, v248, v249
	v_cvt_pk_bf16_f32 v81, v250, v251
	ds_write_b64 v15, v[80:81] offset:1536
	v_cvt_pk_bf16_f32 v76, v108, v109
	v_cvt_pk_bf16_f32 v77, v110, v111
	ds_write_b64 v15, v[76:77] offset:0
	s_waitcnt lgkmcnt(0)
	ds_read_b64_tr_b16 v[112:113], v14 offset:0
	ds_read_b64 v[114:115], v15 offset:1536
	s_waitcnt lgkmcnt(0)
	v_mfma_f32_16x16x16_bf16 v[104:107], v[112:113], v[114:115], 0
	s_nop 7
	v_cvt_pk_bf16_f32 v76, v104, v105
	v_cvt_pk_bf16_f32 v77, v106, v107
	ds_write_b64 v19, v[76:77] offset:8704
	s_nop 0
; #define LAS __attribute__((address_space(3)))
; __device__ __forceinline__ unsigned pk_bf16(float lo, float hi) { const f32x2_t f = {lo, hi}; return __builtin_bit_cast(unsigned, __builtin_convertvector(f, bf16x2_t)); }
; __device__ __forceinline__ void lds_barrier() { asm volatile("s_waitcnt lgkmcnt(0)" ::: "memory"); __builtin_amdgcn_s_barrier(); asm volatile("" ::: "memory"); }
; __device__ __forceinline__ void phase_scan2(const Params& p, int l, LAS unsigned char* lds) {
;     ...
;         auto consume = [&](int c, LAS const unsigned char* sl) {
;             const bf16x8 s0 = __builtin_bit_cast(bf16x8, (u32x4){pk_bf16(ST[0][0], ST[0][1]), pk_bf16(ST[0][2], ST[0][3]), pk_bf16(ST[1][0], ST[1][1]), pk_bf16(ST[1][2], ST[1][3])});
;             const bf16x8 s1 = __builtin_bit_cast(bf16x8, (u32x4){pk_bf16(ST[2][0], ST[2][1]), pk_bf16(ST[2][2], ST[2][3]), pk_bf16(ST[3][0], ST[3][1]), pk_bf16(ST[3][2], ST[3][3])});
;             const bf16x8 at0 = *(LAS const bf16x8*)(sl + SC_AT + (fr * 32 + fq * 8) * 2), at1 = *(LAS const bf16x8*)(sl + SC_AT + ((16 + fr) * 32 + fq * 8) * 2);
;             const bf16x8 rt0 = *(LAS const bf16x8*)(sl + SC_RT + (fr * 32 + fq * 8) * 2), rt1 = *(LAS const bf16x8*)(sl + SC_RT + ((16 + fr) * 32 + fq * 8) * 2);
;             const int mo = (fr * 16 + 4 * fq) * 2;
;             const bf16x8 vf = frag4(sl + SC_VP + mo), akf = frag4(sl + SC_AK + mo), xf = frag4(sl + SC_X + mo), rbf = frag4(sl + SC_RB + mo), rkf = frag4(sl + SC_RK + mo);
;             const f32x4 z = (f32x4){0.f, 0.f, 0.f, 0.f};
;     ...
;         for (int rd = 0; rd < NRD; ++rd) {
;             if (wid == 0) {
; #pragma unroll 1
;                 for (int q = 0; q < SC_NP; ++q) { const int c = rd * SC_NP + q; if (c < NCH) consume(c, lds + ((rd & 1) * SC_NP + q) * SC_SLOT); }
;             } else if (wid >= 3) {
;                 const int cb = (rd + 1) * SC_NP + pw, cn = cb + SC_NP;
;                 if (cb < NCH) pbuild(cb, lds + (((rd + 1) & 1) * SC_NP + pw) * SC_SLOT, scr, cn < NCH ? cn : -1);
;             }
;             lds_barrier();
;         }
.Lsc_p_skip:
	s_add_u32 s58, s58, 6
	s_sub_u32 s56, 66048, s56
	s_add_u32 s50, s50, 3072
	s_addc_u32 s51, s51, 0
	s_add_u32 s42, s42, 1
	s_waitcnt lgkmcnt(0)
	s_barrier
	s_cmp_le_u32 s42, 43
	s_cbranch_scc1 .Lsc_p_loop
	s_branch .Lsc_job_end
.Lsc_consumer:
	v_mov_b32_e32 v8, 0
	v_mov_b32_e32 v9, 0
	v_mov_b32_e32 v10, 0
	v_mov_b32_e32 v11, 0
	v_mov_b32_e32 v16, 0
	v_mov_b32_e32 v17, 0
	v_mov_b32_e32 v18, 0
	v_mov_b32_e32 v19, 0
	v_mov_b32_e32 v20, 0
	v_mov_b32_e32 v21, 0
	v_mov_b32_e32 v22, 0
	v_mov_b32_e32 v23, 0
	v_mov_b32_e32 v24, 0
	v_mov_b32_e32 v25, 0
	v_mov_b32_e32 v26, 0
	v_mov_b32_e32 v27, 0
	v_lshlrev_b32_e32 v113, 6, v1
	v_lshl_add_u32 v113, v2, 4, v113
	v_lshlrev_b32_e32 v114, 4, v2
	v_add_u32_e32 v114, 10752, v114
	v_lshrrev_b32_e32 v4, 2, v1
	v_lshl_add_u32 v4, v2, 2, v4
	v_and_b32_e32 v115, 3, v1
	v_lshlrev_b32_e32 v115, 3, v115
	v_lshl_add_u32 v115, v4, 7, v115
	v_add_u32_e32 v115, 4096, v115
	v_lshlrev_b32_e32 v116, 12, v2
	v_lshl_add_u32 v116, v1, 1, v116
	s_mul_i32 s0, s54, 4096
	s_lshl_b32 s0, s0, 10
	s_lshl_b32 s14, s52, 7
	s_lshl_b32 s15, s53, 5
	s_add_u32 s0, s0, s14
	s_add_u32 s0, s0, s15
	s_add_u32 s0, s0, 0x5000000
	s_add_u32 s48, s74, s0
	s_addc_u32 s49, s75, 0
	s_mov_b32 s42, 0
	s_mov_b32 s58, 0
	s_mov_b32 s56, 0
	s_branch .Lsc_c_bar

; __device__ __forceinline__ void phase_scan2(const Params& p, int l, LAS unsigned char* lds) {
;     ...
;         auto consume = [&](int c, LAS const unsigned char* sl) {
;             const bf16x8 s0 = __builtin_bit_cast(bf16x8, (u32x4){pk_bf16(ST[0][0], ST[0][1]), pk_bf16(ST[0][2], ST[0][3]), pk_bf16(ST[1][0], ST[1][1]), pk_bf16(ST[1][2], ST[1][3])});
;             const bf16x8 s1 = __builtin_bit_cast(bf16x8, (u32x4){pk_bf16(ST[2][0], ST[2][1]), pk_bf16(ST[2][2], ST[2][3]), pk_bf16(ST[3][0], ST[3][1]), pk_bf16(ST[3][2], ST[3][3])});
;             const bf16x8 at0 = *(LAS const bf16x8*)(sl + SC_AT + (fr * 32 + fq * 8) * 2), at1 = *(LAS const bf16x8*)(sl + SC_AT + ((16 + fr) * 32 + fq * 8) * 2);
;             const bf16x8 rt0 = *(LAS const bf16x8*)(sl + SC_RT + (fr * 32 + fq * 8) * 2), rt1 = *(LAS const bf16x8*)(sl + SC_RT + ((16 + fr) * 32 + fq * 8) * 2);
;             const int mo = (fr * 16 + 4 * fq) * 2;
;             const bf16x8 vf = frag4(sl + SC_VP + mo), akf = frag4(sl + SC_AK + mo), xf = frag4(sl + SC_X + mo), rbf = frag4(sl + SC_RB + mo), rkf = frag4(sl + SC_RK + mo);
;             const f32x4 z = (f32x4){0.f, 0.f, 0.f, 0.f};
;             f32x4 g = __builtin_amdgcn_mfma_f32_16x16x32_bf16(at0, s0, z, 0, 0, 0);
;             g = __builtin_amdgcn_mfma_f32_16x16x32_bf16(at1, s1, g, 0, 0, 0);
;             g = __builtin_amdgcn_mfma_f32_16x16x32_bf16(akf, vf, g, 0, 0, 0);
;             const f32x4 sa = __builtin_amdgcn_mfma_f32_16x16x32_bf16(xf, cfrag(g), z, 0, 0, 0);
;             const bf16x8 saf = cfrag(sa);
;             f32x4 y = __builtin_amdgcn_mfma_f32_16x16x32_bf16(rt0, s0, z, 0, 0, 0);
;             y = __builtin_amdgcn_mfma_f32_16x16x32_bf16(rt1, s1, y, 0, 0, 0);
;             y = __builtin_amdgcn_mfma_f32_16x16x32_bf16(rbf, saf, y, 0, 0, 0);
;             y = __builtin_amdgcn_mfma_f32_16x16x32_bf16(rkf, vf, y, 0, 0, 0);
; #pragma unroll
;             for (int jt = 0; jt < 4; ++jt) {
;                 const f32x4 wc = *(LAS const f32x4*)(sl + SC_WC + (16 * jt + 4 * fq) * 4);
;                 const bf16x8 bb = frag4(sl + SC_BBT + ((16 * jt + fr) * SC_BS + 4 * fq) * 2), kb = frag4(sl + SC_KBT + ((16 * jt + fr) * SC_BS + 4 * fq) * 2);
;                 f32x4 acc = ST[jt];
;                 acc = __builtin_amdgcn_mfma_f32_16x16x32_bf16(bb, saf, acc, 0, 0, 0);
;                 acc = __builtin_amdgcn_mfma_f32_16x16x32_bf16(kb, vf, acc, 0, 0, 0);
.Lsc_c_chunk:
	s_cmp_ge_u32 s58, 256
	s_cbranch_scc1 .Lsc_c_next
	v_add_u32_e32 v13, s57, v113
	v_add_u32_e32 v78, s57, v6
	v_add_u32_e32 v82, s57, v114
	v_add_u32_e32 v112, s57, v115
	v_add_u32_e32 v118, s57, v7
	ds_read_b128 v[36:39], v13 offset:0
	ds_read_b128 v[44:47], v13 offset:2048
	ds_read_b128 v[40:43], v13 offset:1024
	ds_read_b128 v[48:51], v13 offset:3072
	ds_read_b64 v[14:15], v78 offset:10240
	ds_read_b64_tr_b16 v[88:89], v112 offset:2048
	ds_read_b64_tr_b16 v[90:91], v112 offset:2080
	ds_read_b64_tr_b16 v[92:93], v112 offset:2112
	ds_read_b64_tr_b16 v[94:95], v112 offset:2144
	ds_read_b64_tr_b16 v[52:53], v118 offset:8192
	ds_read_b64_tr_b16 v[58:59], v118 offset:9728
	ds_read_b64_tr_b16 v[54:55], v118 offset:8704
	ds_read_b64_tr_b16 v[56:57], v118 offset:9216
	v_cvt_pk_bf16_f32 v28, v8, v9
	v_cvt_pk_bf16_f32 v29, v10, v11
	v_cvt_pk_bf16_f32 v30, v16, v17
	v_cvt_pk_bf16_f32 v31, v18, v19
	v_cvt_pk_bf16_f32 v32, v20, v21
	v_cvt_pk_bf16_f32 v33, v22, v23
	v_cvt_pk_bf16_f32 v34, v24, v25
	v_cvt_pk_bf16_f32 v35, v26, v27
	s_waitcnt lgkmcnt(12)
	v_mfma_f32_16x16x32_bf16 v[96:99], v[36:39], v[28:31], 0
	s_waitcnt lgkmcnt(11)
	v_mfma_f32_16x16x32_bf16 v[104:107], v[44:47], v[28:31], 0
	ds_read_b64_tr_b16 v[76:77], v112 offset:0
	ds_read_b64_tr_b16 v[80:81], v112 offset:32
	ds_read_b64_tr_b16 v[84:85], v112 offset:64
	ds_read_b64_tr_b16 v[86:87], v112 offset:96
	s_waitcnt lgkmcnt(14)
	v_mfma_f32_16x16x32_bf16 v[96:99], v[40:43], v[32:35], v[96:99]
	s_waitcnt lgkmcnt(13)
	v_mfma_f32_16x16x32_bf16 v[104:107], v[48:51], v[32:35], v[104:107]
	s_waitcnt lgkmcnt(8)
	v_mfma_f32_16x16x16_bf16 v[8:11], v[88:89], v[14:15], v[8:11]
	v_mfma_f32_16x16x16_bf16 v[16:19], v[90:91], v[14:15], v[16:19]
	v_mfma_f32_16x16x16_bf16 v[20:23], v[92:93], v[14:15], v[20:23]
	v_mfma_f32_16x16x16_bf16 v[24:27], v[94:95], v[14:15], v[24:27]
	ds_read_b128 v[60:63], v82 offset:0
	ds_read_b128 v[64:67], v82 offset:64
	ds_read_b128 v[68:71], v82 offset:128
	ds_read_b128 v[72:75], v82 offset:192
	s_waitcnt lgkmcnt(10)
	v_mfma_f32_16x16x16_bf16 v[96:99], v[52:53], v[14:15], v[96:99]
	v_mfma_f32_16x16x16_bf16 v[104:107], v[58:59], v[14:15], v[104:107]
	s_nop 6
	v_cvt_pk_bf16_f32 v108, v96, v97
	v_cvt_pk_bf16_f32 v109, v98, v99
	s_waitcnt lgkmcnt(9)
	s_nop 0
	v_mfma_f32_16x16x16_bf16 v[100:103], v[54:55], v[108:109], 0
	s_nop 7
	v_cvt_pk_bf16_f32 v110, v100, v101
	v_cvt_pk_bf16_f32 v111, v102, v103
	s_waitcnt lgkmcnt(4)
	s_nop 0
	v_mfma_f32_16x16x16_bf16 v[104:107], v[56:57], v[110:111], v[104:107]
	v_mfma_f32_16x16x16_bf16 v[8:11], v[76:77], v[110:111], v[8:11]
	v_mfma_f32_16x16x16_bf16 v[16:19], v[80:81], v[110:111], v[16:19]
	v_mfma_f32_16x16x16_bf16 v[20:23], v[84:85], v[110:111], v[20:23]
	v_mfma_f32_16x16x16_bf16 v[24:27], v[86:87], v[110:111], v[24:27]
	s_nop 3
	v_cvt_pk_bf16_f32 v117, v104, v104
	global_store_short v116, v117, s[48:49] offset:0
	v_cvt_pk_bf16_f32 v117, v105, v105
	global_store_short v116, v117, s[48:49] offset:1024
	v_cvt_pk_bf16_f32 v117, v106, v106
	global_store_short v116, v117, s[48:49] offset:2048
	v_cvt_pk_bf16_f32 v117, v107, v107
	global_store_short v116, v117, s[48:49] offset:3072
	s_waitcnt lgkmcnt(0)
	v_pk_mul_f32 v[8:9], v[8:9], v[60:61]
	v_pk_mul_f32 v[10:11], v[10:11], v[62:63]
	v_pk_mul_f32 v[16:17], v[16:17], v[64:65]
	v_pk_mul_f32 v[18:19], v[18:19], v[66:67]
	v_pk_mul_f32 v[20:21], v[20:21], v[68:69]
	v_pk_mul_f32 v[22:23], v[22:23], v[70:71]
	v_pk_mul_f32 v[24:25], v[24:25], v[72:73]
	v_pk_mul_f32 v[26:27], v[26:27], v[74:75]
	s_nop 1
.Lsc_c_next:
	s_add_u32 s58, s58, 1
	s_add_u32 s48, s48, 0x4000
	s_addc_u32 s49, s49, 0
	s_add_u32 s57, s57, 11008
	s_add_u32 s59, s59, 1
	s_cmp_lt_u32 s59, 6
	s_cbranch_scc1 .Lsc_c_chunk
	s_sub_u32 s56, 66048, s56
.Lsc_c_bar:
	s_add_u32 s42, s42, 1
	s_waitcnt lgkmcnt(0)
	s_barrier
	s_cmp_le_u32 s42, 43
	s_cbranch_scc1 .Lsc_c_loop
	s_branch .Lsc_job_end

; __device__ __forceinline__ void lds_barrier() { asm volatile("s_waitcnt lgkmcnt(0)" ::: "memory"); __builtin_amdgcn_s_barrier(); asm volatile("" ::: "memory"); }
; __device__ __forceinline__ void phase_scan2(const Params& p, int l, LAS unsigned char* lds) {
;     ...
;         for (int rd = 0; rd < NRD; ++rd) {
;             if (wid == 0) {
; #pragma unroll 1
;                 for (int q = 0; q < SC_NP; ++q) { const int c = rd * SC_NP + q; if (c < NCH) consume(c, lds + ((rd & 1) * SC_NP + q) * SC_SLOT); }
;             } else if (wid >= 3) {
;                 const int cb = (rd + 1) * SC_NP + pw, cn = cb + SC_NP;
;                 if (cb < NCH) pbuild(cb, lds + (((rd + 1) & 1) * SC_NP + pw) * SC_SLOT, scr, cn < NCH ? cn : -1);
;             }
;             lds_barrier();
;         }
.Lsc_i_loop:
	s_add_u32 s42, s42, 1
	s_barrier
	s_cmp_le_u32 s42, 43
	s_cbranch_scc1 .Lsc_i_loop
